# prologue-fifth-transpose-items-spread-one-per-CU
# speedup vs baseline: 1.0120x; 1.0090x over previous
.LBB0_155:
	s_andn2_b64 vcc, exec, s[0:1]
	s_cbranch_vccnz .LBB0_271
	v_ashrrev_i32_e32 v66, 6, v245
	v_readlane_b32 s0, v253, 49
	v_and_b32_e32 v64, 63, v245
	v_readlane_b32 s1, v253, 50
	v_add_u32_e32 v65, s0, v66
	s_movk_i32 s0, 0x2080
	v_cmp_gt_i32_e32 vcc, s0, v65
	v_lshlrev_b32_e32 v68, 2, v64
	s_and_saveexec_b64 s[0:1], vcc
	s_cbranch_execz .LBB0_259
	v_and_b32_e32 v70, 48, v245
	v_and_b32_e32 v72, 60, v68
	v_readlane_b32 s2, v253, 51
	s_mov_b64 s[28:29], 0
	v_lshlrev_b32_e32 v74, 2, v72
	v_add_u32_e32 v67, s2, v66
	v_lshlrev_b32_e32 v76, 1, v70
	v_mov_b32_e32 v69, v65
	s_cmpk_eq_u32 s34, 0x800
	s_cbranch_scc0 .Litem_noperm
	v_readlane_b32 s4, v253, 49
	s_nop 3
	s_lshr_b32 s4, s4, 3
	v_lshl_add_u32 v69, v66, 8, s4
	v_add_u32_e32 v67, 0xffffe080, v69
.Litem_noperm:
	s_branch .LBB0_160
.LBB0_158:
	s_or_b64 exec, exec, s[36:37]
	v_add_u32_e32 v0, v0, v71
